# phase-0 sample-window conversion with 32-row units: every wave takes a unit and issues its 64 row loads in one batch (variant of the LDS-transposed rewrite)
# baseline (speedup 1.0000x reference)
.LBB0_202:
	s_or_b64 exec, exec, s[4:5]
	s_mov_b32 s3, 0x440000
	v_cmp_gt_i32_e32 vcc, s3, v72
	s_and_saveexec_b64 s[4:5], vcc
	s_cbranch_execz .LBB0_213
	s_add_u32 s6, s30, 0x3ea53000
	s_addc_u32 s7, s31, 0
	s_add_u32 s88, s30, 0x3e1d3000
	s_addc_u32 s89, s31, 0
	s_mov_b64 s[20:21], s[0:1]
	s_load_dwordx2 s[20:21], s[20:21], 0x18
	s_movk_i32 s23, 0x7fff
	v_lshrrev_b32_e32 v1, 6, v0
	s_nop 0
	v_readfirstlane_b32 s82, v1
	s_nop 3
	s_lshl_b32 s87, s2, 3
	s_add_i32 s87, s87, s82
	s_lshr_b32 s84, s16, 6
	v_lshlrev_b32_e32 v6, 2, v146
	v_lshlrev_b32_e32 v7, 1, v146
	v_mov_b32_e32 v5, 0
	s_lshl_b32 s85, s82, 14
	v_mul_u32_u24_e32 v8, 0x48, v146
	v_add_u32_e32 v8, s85, v8
	v_lshrrev_b32_e32 v1, 2, v146
	v_and_b32_e32 v2, 3, v146
	v_mul_u32_u24_e32 v9, 0x48, v1
	v_lshl_add_u32 v9, v2, 4, v9
	v_add_u32_e32 v9, s85, v9
	v_mul_u32_u24_e32 v10, 0x440, v1
	v_lshl_add_u32 v10, v2, 4, v10
	v_mul_u32_u24_e32 v11, 0x440, v146
	v_mov_b32_e32 v12, 0
	v_mov_b32_e32 v13, 0
	s_waitcnt lgkmcnt(0)
	s_mov_b32 s83, s87
.Lp0_sw_unit:
	s_cmpk_ge_u32 s83, 0x800
	s_cbranch_scc1 .Lp0_sw_zero
	s_lshr_b32 s80, s83, 4
	s_and_b32 s81, s83, 15
	s_lshr_b32 s76, s80, 2
	s_lshl_b32 s76, s76, 20
	s_lshl_b32 s77, s81, 16
	s_add_i32 s76, s76, s77
	s_and_b32 s77, s80, 3
	s_lshl_b32 s77, s77, 8
	s_add_i32 s76, s76, s77
	s_add_u32 s76, s20, s76
	s_addc_u32 s77, s21, 0
	s_mul_i32 s78, s80, 0x220
	s_lshl_b32 s79, s81, 5
	s_add_i32 s78, s78, s79
	s_lshl_b32 s78, s78, 7
	s_add_u32 s78, s88, s78
	s_addc_u32 s79, s89, 0
	s_mul_i32 s94, s80, 0x11000
	s_lshl_b32 s95, s81, 6
	s_add_i32 s94, s94, s95
	s_add_u32 s94, s6, s94
	s_addc_u32 s95, s7, 0
	s_nop 4
	global_load_dword v164, v6, s[76:77]
	global_load_dword v165, v6, s[76:77] offset:1024
	global_load_dword v166, v6, s[76:77] offset:2048
	global_load_dword v167, v6, s[76:77] offset:3072
	s_add_u32 s76, s76, 0x1000
	s_addc_u32 s77, s77, 0
	s_nop 4
	global_load_dword v168, v6, s[76:77]
	global_load_dword v169, v6, s[76:77] offset:1024
	global_load_dword v170, v6, s[76:77] offset:2048
	global_load_dword v171, v6, s[76:77] offset:3072
	s_add_u32 s76, s76, 0x1000
	s_addc_u32 s77, s77, 0
	s_nop 4
	global_load_dword v172, v6, s[76:77]
	global_load_dword v173, v6, s[76:77] offset:1024
	global_load_dword v174, v6, s[76:77] offset:2048
	global_load_dword v175, v6, s[76:77] offset:3072
	s_add_u32 s76, s76, 0x1000
	s_addc_u32 s77, s77, 0
	s_nop 4
	global_load_dword v176, v6, s[76:77]
	global_load_dword v177, v6, s[76:77] offset:1024
	global_load_dword v178, v6, s[76:77] offset:2048
	global_load_dword v179, v6, s[76:77] offset:3072
	s_add_u32 s76, s76, 0x1000
	s_addc_u32 s77, s77, 0
	s_nop 4
	global_load_dword v180, v6, s[76:77]
	global_load_dword v181, v6, s[76:77] offset:1024
	global_load_dword v182, v6, s[76:77] offset:2048
	global_load_dword v183, v6, s[76:77] offset:3072
	s_add_u32 s76, s76, 0x1000
	s_addc_u32 s77, s77, 0
	s_nop 4
	global_load_dword v184, v6, s[76:77]
	global_load_dword v185, v6, s[76:77] offset:1024
	global_load_dword v186, v6, s[76:77] offset:2048
	global_load_dword v187, v6, s[76:77] offset:3072
	s_add_u32 s76, s76, 0x1000
	s_addc_u32 s77, s77, 0
	s_nop 4
	global_load_dword v188, v6, s[76:77]
	global_load_dword v189, v6, s[76:77] offset:1024
	global_load_dword v190, v6, s[76:77] offset:2048
	global_load_dword v191, v6, s[76:77] offset:3072
	s_add_u32 s76, s76, 0x1000
	s_addc_u32 s77, s77, 0
	s_nop 4
	global_load_dword v192, v6, s[76:77]
	global_load_dword v193, v6, s[76:77] offset:1024
	global_load_dword v194, v6, s[76:77] offset:2048
	global_load_dword v195, v6, s[76:77] offset:3072
	s_add_u32 s76, s76, 0x1000
	s_addc_u32 s77, s77, 0
	s_nop 4
	global_load_dword v196, v6, s[76:77]
	global_load_dword v197, v6, s[76:77] offset:1024
	global_load_dword v198, v6, s[76:77] offset:2048
	global_load_dword v199, v6, s[76:77] offset:3072
	s_add_u32 s76, s76, 0x1000
	s_addc_u32 s77, s77, 0
	s_nop 4
	global_load_dword v200, v6, s[76:77]
	global_load_dword v201, v6, s[76:77] offset:1024
	global_load_dword v202, v6, s[76:77] offset:2048
	global_load_dword v203, v6, s[76:77] offset:3072
	s_add_u32 s76, s76, 0x1000
	s_addc_u32 s77, s77, 0
	s_nop 4
	global_load_dword v204, v6, s[76:77]
	global_load_dword v205, v6, s[76:77] offset:1024
	global_load_dword v206, v6, s[76:77] offset:2048
	global_load_dword v207, v6, s[76:77] offset:3072
	s_add_u32 s76, s76, 0x1000
	s_addc_u32 s77, s77, 0
	s_nop 4
	global_load_dword v208, v6, s[76:77]
	global_load_dword v209, v6, s[76:77] offset:1024
	global_load_dword v210, v6, s[76:77] offset:2048
	global_load_dword v211, v6, s[76:77] offset:3072
	s_add_u32 s76, s76, 0x1000
	s_addc_u32 s77, s77, 0
	s_nop 4
	global_load_dword v212, v6, s[76:77]
	global_load_dword v213, v6, s[76:77] offset:1024
	global_load_dword v214, v6, s[76:77] offset:2048
	global_load_dword v215, v6, s[76:77] offset:3072
	s_add_u32 s76, s76, 0x1000
	s_addc_u32 s77, s77, 0
	s_nop 4
	global_load_dword v216, v6, s[76:77]
	global_load_dword v217, v6, s[76:77] offset:1024
	global_load_dword v218, v6, s[76:77] offset:2048
	global_load_dword v219, v6, s[76:77] offset:3072
	s_add_u32 s76, s76, 0x1000
	s_addc_u32 s77, s77, 0
	s_nop 4
	global_load_dword v220, v6, s[76:77]
	global_load_dword v221, v6, s[76:77] offset:1024
	global_load_dword v222, v6, s[76:77] offset:2048
	global_load_dword v223, v6, s[76:77] offset:3072
	s_add_u32 s76, s76, 0x1000
	s_addc_u32 s77, s77, 0
	s_nop 4
	global_load_dword v224, v6, s[76:77]
	global_load_dword v225, v6, s[76:77] offset:1024
	global_load_dword v226, v6, s[76:77] offset:2048
	global_load_dword v227, v6, s[76:77] offset:3072
	s_add_u32 s76, s76, 0x1000
	s_addc_u32 s77, s77, 0
	s_waitcnt vmcnt(62)
	v_bfe_u32 v1, v164, 16, 1
	v_bfe_u32 v2, v165, 16, 1
	v_add3_u32 v164, v164, v1, s23
	v_add3_u32 v165, v165, v2, s23
	s_waitcnt vmcnt(60)
	v_bfe_u32 v1, v166, 16, 1
	v_bfe_u32 v2, v167, 16, 1
	v_add3_u32 v166, v166, v1, s23
	v_add3_u32 v167, v167, v2, s23
	s_waitcnt vmcnt(58)
	v_bfe_u32 v1, v168, 16, 1
	v_bfe_u32 v2, v169, 16, 1
	v_add3_u32 v168, v168, v1, s23
	v_add3_u32 v169, v169, v2, s23
	s_waitcnt vmcnt(56)
	v_bfe_u32 v1, v170, 16, 1
	v_bfe_u32 v2, v171, 16, 1
	v_add3_u32 v170, v170, v1, s23
	v_add3_u32 v171, v171, v2, s23
	s_waitcnt vmcnt(54)
	v_bfe_u32 v1, v172, 16, 1
	v_bfe_u32 v2, v173, 16, 1
	v_add3_u32 v172, v172, v1, s23
	v_add3_u32 v173, v173, v2, s23
	s_waitcnt vmcnt(52)
	v_bfe_u32 v1, v174, 16, 1
	v_bfe_u32 v2, v175, 16, 1
	v_add3_u32 v174, v174, v1, s23
	v_add3_u32 v175, v175, v2, s23
	s_waitcnt vmcnt(50)
	v_bfe_u32 v1, v176, 16, 1
	v_bfe_u32 v2, v177, 16, 1
	v_add3_u32 v176, v176, v1, s23
	v_add3_u32 v177, v177, v2, s23
	s_waitcnt vmcnt(48)
	v_bfe_u32 v1, v178, 16, 1
	v_bfe_u32 v2, v179, 16, 1
	v_add3_u32 v178, v178, v1, s23
	v_add3_u32 v179, v179, v2, s23
	s_waitcnt vmcnt(46)
	v_bfe_u32 v1, v180, 16, 1
	v_bfe_u32 v2, v181, 16, 1
	v_add3_u32 v180, v180, v1, s23
	v_add3_u32 v181, v181, v2, s23
	s_waitcnt vmcnt(44)
	v_bfe_u32 v1, v182, 16, 1
	v_bfe_u32 v2, v183, 16, 1
	v_add3_u32 v182, v182, v1, s23
	v_add3_u32 v183, v183, v2, s23
	s_waitcnt vmcnt(42)
	v_bfe_u32 v1, v184, 16, 1
	v_bfe_u32 v2, v185, 16, 1
	v_add3_u32 v184, v184, v1, s23
	v_add3_u32 v185, v185, v2, s23
	s_waitcnt vmcnt(40)
	v_bfe_u32 v1, v186, 16, 1
	v_bfe_u32 v2, v187, 16, 1
	v_add3_u32 v186, v186, v1, s23
	v_add3_u32 v187, v187, v2, s23
	s_waitcnt vmcnt(38)
	v_bfe_u32 v1, v188, 16, 1
	v_bfe_u32 v2, v189, 16, 1
	v_add3_u32 v188, v188, v1, s23
	v_add3_u32 v189, v189, v2, s23
	s_waitcnt vmcnt(36)
	v_bfe_u32 v1, v190, 16, 1
	v_bfe_u32 v2, v191, 16, 1
	v_add3_u32 v190, v190, v1, s23
	v_add3_u32 v191, v191, v2, s23
	s_waitcnt vmcnt(34)
	v_bfe_u32 v1, v192, 16, 1
	v_bfe_u32 v2, v193, 16, 1
	v_add3_u32 v192, v192, v1, s23
	v_add3_u32 v193, v193, v2, s23
	s_waitcnt vmcnt(32)
	v_bfe_u32 v1, v194, 16, 1
	v_bfe_u32 v2, v195, 16, 1
	v_add3_u32 v194, v194, v1, s23
	v_add3_u32 v195, v195, v2, s23
	s_waitcnt vmcnt(30)
	v_bfe_u32 v1, v196, 16, 1
	v_bfe_u32 v2, v197, 16, 1
	v_add3_u32 v196, v196, v1, s23
	v_add3_u32 v197, v197, v2, s23
	s_waitcnt vmcnt(28)
	v_bfe_u32 v1, v198, 16, 1
	v_bfe_u32 v2, v199, 16, 1
	v_add3_u32 v198, v198, v1, s23
	v_add3_u32 v199, v199, v2, s23
	s_waitcnt vmcnt(26)
	v_bfe_u32 v1, v200, 16, 1
	v_bfe_u32 v2, v201, 16, 1
	v_add3_u32 v200, v200, v1, s23
	v_add3_u32 v201, v201, v2, s23
	s_waitcnt vmcnt(24)
	v_bfe_u32 v1, v202, 16, 1
	v_bfe_u32 v2, v203, 16, 1
	v_add3_u32 v202, v202, v1, s23
	v_add3_u32 v203, v203, v2, s23
	s_waitcnt vmcnt(22)
	v_bfe_u32 v1, v204, 16, 1
	v_bfe_u32 v2, v205, 16, 1
	v_add3_u32 v204, v204, v1, s23
	v_add3_u32 v205, v205, v2, s23
	s_waitcnt vmcnt(20)
	v_bfe_u32 v1, v206, 16, 1
	v_bfe_u32 v2, v207, 16, 1
	v_add3_u32 v206, v206, v1, s23
	v_add3_u32 v207, v207, v2, s23
	s_waitcnt vmcnt(18)
	v_bfe_u32 v1, v208, 16, 1
	v_bfe_u32 v2, v209, 16, 1
	v_add3_u32 v208, v208, v1, s23
	v_add3_u32 v209, v209, v2, s23
	s_waitcnt vmcnt(16)
	v_bfe_u32 v1, v210, 16, 1
	v_bfe_u32 v2, v211, 16, 1
	v_add3_u32 v210, v210, v1, s23
	v_add3_u32 v211, v211, v2, s23
	s_waitcnt vmcnt(14)
	v_bfe_u32 v1, v212, 16, 1
	v_bfe_u32 v2, v213, 16, 1
	v_add3_u32 v212, v212, v1, s23
	v_add3_u32 v213, v213, v2, s23
	s_waitcnt vmcnt(12)
	v_bfe_u32 v1, v214, 16, 1
	v_bfe_u32 v2, v215, 16, 1
	v_add3_u32 v214, v214, v1, s23
	v_add3_u32 v215, v215, v2, s23
	s_waitcnt vmcnt(10)
	v_bfe_u32 v1, v216, 16, 1
	v_bfe_u32 v2, v217, 16, 1
	v_add3_u32 v216, v216, v1, s23
	v_add3_u32 v217, v217, v2, s23
	s_waitcnt vmcnt(8)
	v_bfe_u32 v1, v218, 16, 1
	v_bfe_u32 v2, v219, 16, 1
	v_add3_u32 v218, v218, v1, s23
	v_add3_u32 v219, v219, v2, s23
	s_waitcnt vmcnt(6)
	v_bfe_u32 v1, v220, 16, 1
	v_bfe_u32 v2, v221, 16, 1
	v_add3_u32 v220, v220, v1, s23
	v_add3_u32 v221, v221, v2, s23
	s_waitcnt vmcnt(4)
	v_bfe_u32 v1, v222, 16, 1
	v_bfe_u32 v2, v223, 16, 1
	v_add3_u32 v222, v222, v1, s23
	v_add3_u32 v223, v223, v2, s23
	s_waitcnt vmcnt(2)
	v_bfe_u32 v1, v224, 16, 1
	v_bfe_u32 v2, v225, 16, 1
	v_add3_u32 v224, v224, v1, s23
	v_add3_u32 v225, v225, v2, s23
	s_waitcnt vmcnt(0)
	v_bfe_u32 v1, v226, 16, 1
	v_bfe_u32 v2, v227, 16, 1
	v_add3_u32 v226, v226, v1, s23
	v_add3_u32 v227, v227, v2, s23
	global_store_short_d16_hi v7, v164, s[78:79]
	ds_write_b16_d16_hi v8, v165
	global_store_short_d16_hi v7, v166, s[78:79] offset:128
	ds_write_b16_d16_hi v8, v167 offset:2
	global_store_short_d16_hi v7, v168, s[78:79] offset:256
	ds_write_b16_d16_hi v8, v169 offset:4
	global_store_short_d16_hi v7, v170, s[78:79] offset:384
	ds_write_b16_d16_hi v8, v171 offset:6
	global_store_short_d16_hi v7, v172, s[78:79] offset:512
	ds_write_b16_d16_hi v8, v173 offset:8
	global_store_short_d16_hi v7, v174, s[78:79] offset:640
	ds_write_b16_d16_hi v8, v175 offset:10
	global_store_short_d16_hi v7, v176, s[78:79] offset:768
	ds_write_b16_d16_hi v8, v177 offset:12
	global_store_short_d16_hi v7, v178, s[78:79] offset:896
	ds_write_b16_d16_hi v8, v179 offset:14
	global_store_short_d16_hi v7, v180, s[78:79] offset:1024
	ds_write_b16_d16_hi v8, v181 offset:16
	global_store_short_d16_hi v7, v182, s[78:79] offset:1152
	ds_write_b16_d16_hi v8, v183 offset:18
	global_store_short_d16_hi v7, v184, s[78:79] offset:1280
	ds_write_b16_d16_hi v8, v185 offset:20
	global_store_short_d16_hi v7, v186, s[78:79] offset:1408
	ds_write_b16_d16_hi v8, v187 offset:22
	global_store_short_d16_hi v7, v188, s[78:79] offset:1536
	ds_write_b16_d16_hi v8, v189 offset:24
	global_store_short_d16_hi v7, v190, s[78:79] offset:1664
	ds_write_b16_d16_hi v8, v191 offset:26
	global_store_short_d16_hi v7, v192, s[78:79] offset:1792
	ds_write_b16_d16_hi v8, v193 offset:28
	global_store_short_d16_hi v7, v194, s[78:79] offset:1920
	ds_write_b16_d16_hi v8, v195 offset:30
	global_store_short_d16_hi v7, v196, s[78:79] offset:2048
	ds_write_b16_d16_hi v8, v197 offset:32
	global_store_short_d16_hi v7, v198, s[78:79] offset:2176
	ds_write_b16_d16_hi v8, v199 offset:34
	global_store_short_d16_hi v7, v200, s[78:79] offset:2304
	ds_write_b16_d16_hi v8, v201 offset:36
	global_store_short_d16_hi v7, v202, s[78:79] offset:2432
	ds_write_b16_d16_hi v8, v203 offset:38
	global_store_short_d16_hi v7, v204, s[78:79] offset:2560
	ds_write_b16_d16_hi v8, v205 offset:40
	global_store_short_d16_hi v7, v206, s[78:79] offset:2688
	ds_write_b16_d16_hi v8, v207 offset:42
	global_store_short_d16_hi v7, v208, s[78:79] offset:2816
	ds_write_b16_d16_hi v8, v209 offset:44
	global_store_short_d16_hi v7, v210, s[78:79] offset:2944
	ds_write_b16_d16_hi v8, v211 offset:46
	global_store_short_d16_hi v7, v212, s[78:79] offset:3072
	ds_write_b16_d16_hi v8, v213 offset:48
	global_store_short_d16_hi v7, v214, s[78:79] offset:3200
	ds_write_b16_d16_hi v8, v215 offset:50
	global_store_short_d16_hi v7, v216, s[78:79] offset:3328
	ds_write_b16_d16_hi v8, v217 offset:52
	global_store_short_d16_hi v7, v218, s[78:79] offset:3456
	ds_write_b16_d16_hi v8, v219 offset:54
	global_store_short_d16_hi v7, v220, s[78:79] offset:3584
	ds_write_b16_d16_hi v8, v221 offset:56
	global_store_short_d16_hi v7, v222, s[78:79] offset:3712
	ds_write_b16_d16_hi v8, v223 offset:58
	global_store_short_d16_hi v7, v224, s[78:79] offset:3840
	ds_write_b16_d16_hi v8, v225 offset:60
	global_store_short_d16_hi v7, v226, s[78:79] offset:3968
	ds_write_b16_d16_hi v8, v227 offset:62
	s_waitcnt lgkmcnt(0)
	ds_read_b64 v[164:165], v9
	ds_read_b64 v[166:167], v9 offset:8
	ds_read_b64 v[168:169], v9 offset:1152
	ds_read_b64 v[170:171], v9 offset:1160
	ds_read_b64 v[172:173], v9 offset:2304
	ds_read_b64 v[174:175], v9 offset:2312
	ds_read_b64 v[176:177], v9 offset:3456
	ds_read_b64 v[178:179], v9 offset:3464
	s_waitcnt lgkmcnt(6)
	global_store_dwordx4 v10, v[164:167], s[94:95]
	s_add_u32 s94, s94, 0x4400
	s_addc_u32 s95, s95, 0
	s_nop 4
	s_waitcnt lgkmcnt(4)
	global_store_dwordx4 v10, v[168:171], s[94:95]
	s_add_u32 s94, s94, 0x4400
	s_addc_u32 s95, s95, 0
	s_nop 4
	s_waitcnt lgkmcnt(2)
	global_store_dwordx4 v10, v[172:175], s[94:95]
	s_add_u32 s94, s94, 0x4400
	s_addc_u32 s95, s95, 0
	s_nop 4
	s_waitcnt lgkmcnt(0)
	global_store_dwordx4 v10, v[176:179], s[94:95]
	s_add_u32 s94, s94, 0x4400
	s_addc_u32 s95, s95, 0
	s_nop 4
	s_add_i32 s83, s83, s84
	s_branch .Lp0_sw_unit
.Lp0_sw_zero:
	s_mov_b32 s83, s87
